# mixer-B FAST loop: all 8 waves take the same-tile QK/softmax/PV path (no lagged-PV half)
# speedup vs baseline: 1.0097x; 1.0071x over previous
; template <int MODE, int NQ, int TS, bool FAST = false> ...
;     ...
;   const int lane = tid & 63, wave = tid >> 6, r32 = lane & 31, hh = lane >> 5;
;   constexpr float C2 = 0.125f * LOG2E;
;   constexpr int NS = 6;
;   bf16x8 qf[NQ][4];
; #pragma unroll
;   for (int nq = 0; nq < NQ; ++nq) { const bf16_t* qp = proj + (size_t)(seq_base + TS * (q0w + 32 * nq + r32)) * ld + qoff + hh * 8;
; #pragma unroll
;     for (int ks = 0; ks < 4; ++ks) qf[nq][ks] = *(const bf16x8*)(qp + ks * 16); }
;   f32x16 o[NQ][2];
;   float m2[NQ], l[NQ];
; #pragma unroll
;   for (int nq = 0; nq < NQ; ++nq) {
;     if (MODE == 0) {
;       const size_t tok = (size_t)(seq_base + q0w + 32 * nq + r32);
;       const bf16_t* po = part_o + tok * 512 + ooff + 4 * hh; const float* pm = part_ml + (tok * 8 + (ooff >> 6)) * 2;
;       m2[nq] = pm[0]; l[nq] = hh ? 0.f : pm[1];
; #pragma unroll
;       for (int g = 0; g < 4; ++g) { const uint2 a = *(const uint2*)(po + 8 * g), b = *(const uint2*)(po + 32 + 8 * g);
;         o[nq][0][4 * g] = bflo(a.x); o[nq][0][4 * g + 1] = bfhi(a.x); o[nq][0][4 * g + 2] = bflo(a.y); o[nq][0][4 * g + 3] = bfhi(a.y);
;         o[nq][1][4 * g] = bflo(b.x); o[nq][1][4 * g + 1] = bfhi(b.x); o[nq][1][4 * g + 2] = bflo(b.y); o[nq][1][4 * g + 3] = bfhi(b.y); }
;     } else {
;       m2[nq] = (MODE == 2) ? sink2 : -1e30f; l[nq] = 0.f;
; #pragma unroll
;       for (int r = 0; r < 16; ++r) { o[nq][0][r] = 0.f; o[nq][1][r] = 0.f; }
;     }
;   }
;   PG8_LAS unsigned char* L = (PG8_LAS unsigned char*)lds;
;   const int kkey_ = wave * 8 + (lane >> 3);
;   const bf16_t* kg = proj + (size_t)(seq_base + TS * kkey_) * ld + koff + (((lane & 7) ^ ((kkey_ >> 1) & 7)) * 8);
;   const bf16_t* vg = proj + (size_t)(seq_base + TS * ((wave & 3) * 16 + (lane >> 2))) * ld + voff + ((wave >> 2) * 4 + (lane & 3)) * 8;
;   const unsigned sdst = (unsigned)__builtin_amdgcn_readfirstlane(wave * 1024);
;     ...
;   const int ktl = kt1 - 1;
;   constexpr int TAB_OFF = 6 * 16384, TAB_N = (MODE == 3) ? 640 : 1024, TAB_ZERO = TAB_N / 2;
;   if (MODE == 0 || MODE == 3) {
;     float* tab = (float*)(lds + TAB_OFF);
;     for (int e = tid; e < TAB_N; e += 512) {
;       const int oo = e - TAB_ZERO, aa = oo < 0 ? -oo : oo;
;       if (MODE == 0) {
;         const int c = (aa <= 64 ? 1 : 0) + (((oo & 3) == 0 && aa <= 256) ? 1 : 0) + (((oo & 15) == 0 && aa <= 256) ? 1 : 0);
.LBB0_434:
	s_andn2_saveexec_b64 s[0:1], s[0:1]
	s_cbranch_execz .LBB0_364
	v_mov_b32_e32 v8, v222
	v_mov_b32_e32 v3, v1
	v_and_b32_e32 v9, 31, v8
	v_bfe_u32 v182, v8, 5, 1
	v_add_u32_e32 v168, v9, v37
	v_lshlrev_b32_e32 v2, 4, v182
	v_lshl_add_u64 v[2:3], v[38:39], 0, v[2:3]
	s_movk_i32 s4, 0x1200
	v_add_u32_e32 v166, 32, v168
	v_mad_i64_i32 v[4:5], s[8:9], v168, s4, v[2:3]
	v_mad_i64_i32 v[2:3], s[8:9], v166, s4, v[2:3]
	global_load_dwordx4 v[130:133], v[4:5], off offset:3072
	global_load_dwordx4 v[134:137], v[4:5], off offset:3104
	global_load_dwordx4 v[138:141], v[4:5], off offset:3136
	global_load_dwordx4 v[142:145], v[4:5], off offset:3168
	global_load_dwordx4 v[146:149], v[2:3], off offset:3072
	global_load_dwordx4 v[150:153], v[2:3], off offset:3104
	global_load_dwordx4 v[154:157], v[2:3], off offset:3136
	global_load_dwordx4 v[158:161], v[2:3], off offset:3168
	v_ashrrev_i32_e32 v10, 6, v8
	v_bfe_u32 v2, v8, 3, 3
	v_lshl_or_b32 v4, v10, 3, v2
	v_add_u32_e32 v5, s6, v4
	v_lshrrev_b32_e32 v4, 1, v4
	v_mov_b64_e32 v[2:3], s[66:67]
	v_xor_b32_e32 v4, v4, v8
	v_mad_i64_i32 v[2:3], s[8:9], v5, s4, v[2:3]
	s_lshl_b32 s76, s7, 1
	v_lshlrev_b32_e32 v4, 4, v4
	v_lshl_add_u64 v[2:3], v[2:3], 0, s[76:77]
	v_and_b32_e32 v4, 0x70, v4
	v_mov_b32_e32 v5, v1
	v_lshl_add_u64 v[2:3], v[2:3], 0, v[4:5]
	v_lshlrev_b32_e32 v4, 4, v10
	v_and_b32_e32 v4, 48, v4
	v_bfe_u32 v5, v8, 2, 4
	v_add3_u32 v4, v5, s6, v4
	v_and_b32_e32 v11, 3, v8
	s_mov_b32 s4, 0x1ffffffc
	v_mul_i32_i24_e32 v4, 0x900, v4
	v_mov_b32_e32 v5, v1
	v_and_or_b32 v6, v10, s4, v11
	v_lshl_add_u64 v[4:5], v[4:5], 1, s[66:67]
	v_lshlrev_b32_e32 v6, 3, v6
	v_readfirstlane_b32 s4, v10
	s_mov_b64 s[8:9], 0x1000
	v_lshl_add_u64 v[4:5], v[4:5], 0, s[76:77]
	v_ashrrev_i32_e32 v7, 31, v6
	s_lshl_b32 s4, s4, 10
	v_lshl_add_u64 v[172:173], v[2:3], 0, s[8:9]
	v_lshl_add_u64 v[4:5], v[6:7], 1, v[4:5]
	s_mov_b64 s[6:7], 0x1100
	s_mov_b32 m0, s4
	v_lshl_add_u64 v[174:175], v[4:5], 0, s[6:7]
	global_load_lds_dwordx4 v[172:173], off
	s_add_i32 m0, s4, 0x2000
	s_mov_b64 s[6:7], 0x49000
	global_load_lds_dwordx4 v[174:175], off
	v_lshl_add_u64 v[6:7], v[2:3], 0, s[6:7]
	s_add_i32 m0, s4, 0x4000
	s_mov_b64 s[6:7], 0x49100
	global_load_lds_dwordx4 v[6:7], off
	v_lshl_add_u64 v[6:7], v[4:5], 0, s[6:7]
	s_add_i32 m0, s4, 0x6000
	s_mov_b64 s[6:7], 0x91000
	global_load_lds_dwordx4 v[6:7], off
	v_lshl_add_u64 v[6:7], v[2:3], 0, s[6:7]
	s_add_i32 m0, s4, 0x8000
	s_mov_b64 s[6:7], 0x91100
	global_load_lds_dwordx4 v[6:7], off
	v_lshl_add_u64 v[6:7], v[4:5], 0, s[6:7]
	s_add_i32 m0, s4, 0xa000
	s_mov_b64 s[6:7], 0xd9000
	global_load_lds_dwordx4 v[6:7], off
	v_lshl_add_u64 v[2:3], v[2:3], 0, s[6:7]
	s_add_i32 m0, s4, 0xc000
	s_mov_b64 s[6:7], 0xd9100
	global_load_lds_dwordx4 v[2:3], off
	v_lshl_add_u64 v[2:3], v[4:5], 0, s[6:7]
	s_add_i32 m0, s4, 0xe000
	v_bfe_u32 v4, v8, 1, 3
	global_load_lds_dwordx4 v[2:3], off
	v_lshrrev_b32_e32 v3, 1, v8
	v_lshlrev_b32_e32 v2, 7, v9
	v_bitop3_b32 v3, v182, v3, 7 bitop3:0x78
	v_lshl_or_b32 v183, v3, 4, v2
	v_bitop3_b32 v3, v182, v4, 2 bitop3:0x36
	v_lshl_or_b32 v184, v3, 4, v2
	v_bitop3_b32 v3, v182, v4, 4 bitop3:0x36
	v_lshl_or_b32 v186, v3, 4, v2
	v_bitop3_b32 v3, v182, v4, 6 bitop3:0x36
	v_lshl_or_b32 v187, v3, 4, v2
	v_lshlrev_b32_e32 v2, 4, v8
	v_and_b32_e32 v2, 0xc0, v2
	v_lshlrev_b32_e32 v3, 1, v8
	s_waitcnt vmcnt(6) lgkmcnt(0)
	s_barrier
	v_lshl_or_b32 v2, v182, 8, v2
	v_and_b32_e32 v3, 32, v3
	v_lshlrev_b32_e32 v4, 3, v11
	v_mov_b32_e32 v50, v1
	v_mov_b32_e32 v51, v1
	v_or3_b32 v185, v2, v3, v4
	v_cmp_lt_i32_e32 vcc, 7, v10
	v_cmp_gt_i32_e64 s[38:39], 8, v10
	v_mov_b32_e32 v52, v1
	v_mov_b32_e32 v53, v1
	v_mov_b32_e32 v54, v1
	v_mov_b32_e32 v55, v1
	v_mov_b32_e32 v56, v1
	v_mov_b32_e32 v57, v1
	v_mov_b32_e32 v58, v1
	v_mov_b32_e32 v59, v1
	v_mov_b32_e32 v60, v1
	v_mov_b32_e32 v61, v1
	v_mov_b32_e32 v62, v1
	v_mov_b32_e32 v63, v1
	v_mov_b32_e32 v64, v1
	v_mov_b32_e32 v65, v1
	v_mov_b32_e32 v170, 0
	v_mov_b64_e32 v[34:35], v[50:51]
	v_mov_b64_e32 v[18:19], v[50:51]
	v_mov_b64_e32 v[2:3], v[50:51]
	s_movk_i32 s22, 0x1200
	v_ashrrev_i32_e32 v169, 31, v168
	v_ashrrev_i32_e32 v167, 31, v166
	s_add_i32 s6, s5, -1
	s_mov_b32 s12, 0
	v_mov_b64_e32 v[36:37], v[52:53]
	v_mov_b64_e32 v[38:39], v[54:55]
	v_mov_b64_e32 v[40:41], v[56:57]
	v_mov_b64_e32 v[42:43], v[58:59]
	v_mov_b64_e32 v[44:45], v[60:61]
	v_mov_b64_e32 v[46:47], v[62:63]
	v_mov_b64_e32 v[48:49], v[64:65]
	v_mov_b64_e32 v[20:21], v[52:53]
	v_mov_b64_e32 v[22:23], v[54:55]
	v_mov_b64_e32 v[24:25], v[56:57]
	v_mov_b64_e32 v[26:27], v[58:59]
	v_mov_b64_e32 v[28:29], v[60:61]
	v_mov_b64_e32 v[30:31], v[62:63]
	v_mov_b64_e32 v[32:33], v[64:65]
	v_mov_b64_e32 v[4:5], v[52:53]
	v_mov_b64_e32 v[6:7], v[54:55]
	v_mov_b64_e32 v[8:9], v[56:57]
	v_mov_b64_e32 v[10:11], v[58:59]
	v_mov_b64_e32 v[12:13], v[60:61]
	v_mov_b64_e32 v[14:15], v[62:63]
	v_mov_b64_e32 v[16:17], v[64:65]
	s_mov_b32 s9, 0
	s_mov_b32 s7, 0
	v_mov_b32_e32 v171, v170
